# HGRN scan: LDS fragment reads software-pipelined ahead of the MFMA chains, A' fragments shared, decay load first
# speedup vs baseline: 1.0150x; 1.0011x over previous
.LBB0_499:
	s_lshl_b32 s14, s4, 1
	s_or_b32 s14, s14, s11
	s_ashr_i32 s15, s14, 31
	s_lshl_b64 s[14:15], s[14:15], 18
	s_add_u32 s11, s72, s14
	s_addc_u32 s14, s73, s15
	s_lshl_b32 s13, s13, 2
	s_add_u32 s11, s11, s13
	s_addc_u32 s13, s14, 0
	s_lshl_b32 s14, s8, 6
	s_add_u32 s14, s11, s14
	s_addc_u32 s15, s13, 0
	v_lshlrev_b32_e32 v0, 2, v58
	v_lshl_add_u64 v[30:31], s[14:15], 0, v[0:1]
	s_and_b64 s[14:15], exec, s[2:3]
	s_mov_b32 s29, 0
	s_cselect_b32 s28, 0, 0x3f000
	v_lshl_add_u64 v[10:11], v[30:31], 0, s[28:29]
	global_load_dwordx4 v[10:13], v[10:11], off
	s_lshr_b32 s13, s10, 7
	s_lshl_b32 s14, s12, 1
	s_lshl_b32 s38, s13, 4
	s_lshl_b64 s[48:49], s[4:5], 24
	s_cmp_le_u32 s14, s13
	s_cselect_b64 s[30:31], -1, 0
	s_lshl_b32 s39, s12, 5
	s_lshl_b32 s28, s12, 6
	s_or_b32 s40, s14, 1
	v_xor_b32_e32 v0, s8, v63
	s_cmp_lt_u32 s14, s13
	v_lshl_add_u32 v70, v0, 4, v90
	v_xor_b32_e32 v0, v16, v63
	v_lshl_or_b32 v16, s12, 4, v50
	s_cselect_b64 s[34:35], -1, 0
	s_lshl_b32 s12, s40, 4
	s_lshl_b32 s47, s40, 5
	s_and_b64 s[50:51], exec, s[2:3]
	s_cselect_b32 s41, s76, s36
	s_cselect_b32 s40, s77, s33
	s_add_u32 s41, s41, s48
	v_mov_b32_e32 v15, v1
	s_waitcnt vmcnt(22)
	v_or_b32_e32 v18, s39, v50
	s_addc_u32 s40, s40, s49
	v_lshl_add_u32 v71, v0, 4, v92
	v_lshl_add_u64 v[32:33], s[6:7], 0, v[14:15]
	v_or_b32_e32 v0, s38, v50
	s_movk_i32 s6, 0x110
	v_mul_u32_u24_e32 v17, 0x110, v16
	v_mad_u32_u24 v114, v16, s37, 0
	v_lshl_or_b32 v16, s8, 4, v50
	v_mul_u32_u24_e32 v19, 0x110, v18
	v_or_b32_e32 v18, s39, v58
	s_add_u32 s20, s41, s20
	v_mul_lo_u32 v15, v0, s6
	v_mul_lo_u32 v16, v16, s37
	v_cmp_gt_u32_e64 s[4:5], v18, v0
	v_cmp_lt_u32_e64 s[6:7], v18, v0
	v_or_b32_e32 v20, 2, v18
	v_or_b32_e32 v18, 3, v18
	s_addc_u32 s40, s40, 0
	v_add_u32_e32 v115, 0, v16
	v_lshl_add_u32 v16, s8, 5, v94
	s_mulk_i32 s8, 0x880
	s_mulk_i32 s9, 0x110
	v_cmp_gt_u32_e64 s[10:11], v18, v0
	v_or_b32_e32 v18, s12, v50
	s_add_u32 s20, s20, s21
	v_add_u32_e32 v116, s8, v89
	v_add_u32_e32 v117, s9, v89
	v_cmp_gt_u32_e64 s[8:9], v20, v0
	v_mul_u32_u24_e32 v20, 0x110, v18
	v_or_b32_e32 v18, s12, v58
	s_addc_u32 s21, s40, 0
	v_cmp_gt_u32_e64 s[12:13], v18, v0
	v_cmp_lt_u32_e64 s[14:15], v18, v0
	v_or_b32_e32 v21, 2, v18
	v_or_b32_e32 v18, 3, v18
	s_add_u32 s20, s20, s39
	v_mul_lo_u32 v14, v0, s37
	v_cmp_gt_u32_e64 s[16:17], v21, v0
	v_cmp_gt_u32_e64 s[18:19], v18, v0
	s_addc_u32 s21, s21, 0
	v_lshlrev_b32_e32 v0, 1, v50
	v_mov_b32_e32 v18, 0
	s_mov_b32 s46, 1
	v_add_u32_e32 v113, v91, v14
	v_lshl_add_u64 v[34:35], s[20:21], 0, v[0:1]
	v_subrev_u32_e32 v0, s39, v106
	s_sub_i32 s48, 0, s25
	v_or_b32_e32 v118, s38, v58
	v_subrev_u32_e32 v119, s38, v104
	v_or_b32_e32 v120, s39, v74
	s_mov_b32 s49, 62
	v_add_u32_e32 v121, v99, v19
	v_add_u32_e32 v122, v99, v20
	v_add_u32_e32 v123, v100, v17
	v_add_u32_e32 v124, v93, v14
	v_add_u32_e32 v125, v16, v96
	v_add_u32_e32 v126, v99, v15
	s_mov_b32 s50, s29
	v_mov_b32_e32 v19, v18
	v_mov_b32_e32 v20, v18
	v_mov_b32_e32 v21, v18
	v_mov_b32_e32 v14, v18
	v_mov_b32_e32 v15, v18
	v_mov_b32_e32 v16, v18
	v_mov_b32_e32 v17, v18
	s_and_b64 s[94:95], s[2:3], exec
	s_cselect_b32 s93, 0, -1
	v_readfirstlane_b32 s54, v26
	v_readfirstlane_b32 s55, v27
	v_readfirstlane_b32 s56, v28
	v_readfirstlane_b32 s57, v29
	v_readfirstlane_b32 s58, v32
	v_readfirstlane_b32 s59, v33
	v_readfirstlane_b32 s60, v34
	v_readfirstlane_b32 s61, v35
	s_lshl_b32 s94, s24, 1
	s_add_i32 s95, s25, 64
	s_sub_i32 s96, 0xfb8, s25
	s_cmp_eq_u32 s93, 0
	s_cselect_b32 s95, s95, s96
	s_mul_i32 s96, s95, s94
	s_add_u32 s54, s54, s96
	s_addc_u32 s55, s55, 0
	s_mul_i32 s96, s95, 0x4800
	s_add_u32 s56, s56, s96
	s_addc_u32 s57, s57, 0
	s_cmp_eq_u32 s93, 0
	s_cselect_b32 s95, 64, 0xf80
	s_mul_i32 s96, s95, 0x4800
	s_add_u32 s58, s58, s96
	s_addc_u32 s59, s59, 0
	s_and_b32 s96, s93, 0xfc0000
	s_add_u32 s60, s60, s96
	s_addc_u32 s61, s61, 0
	s_lshl_b32 s62, s94, 6
	s_xor_b32 s62, s62, s93
	s_sub_i32 s62, s62, s93
	s_xor_b32 s63, s93, 0x120000
	s_sub_i32 s63, s63, s93
	s_xor_b32 s92, s93, 0x40000
	s_sub_i32 s92, s92, s93
	v_lshlrev_b32_e32 v140, 2, v220
	s_mul_i32 s95, s94, 7
	s_and_b32 s95, s95, s93
	v_add_u32_e32 v140, s95, v140
	s_xor_b32 s95, s94, s93
	s_sub_i32 s95, s95, s93
	v_add_u32_e32 v141, s95, v140
	v_add_u32_e32 v142, s95, v141
	v_add_u32_e32 v143, s95, v142
	v_add_u32_e32 v144, s95, v143
	v_add_u32_e32 v145, s95, v144
	v_add_u32_e32 v146, s95, v145
	v_add_u32_e32 v147, s95, v146
	v_lshlrev_b32_e32 v148, 2, v220
	s_and_b32 s95, s93, 0x1f800
	v_add_u32_e32 v148, s95, v148
	s_xor_b32 s95, s93, 0x4800
	s_sub_i32 s95, s95, s93
	v_add_u32_e32 v149, s95, v148
	v_add_u32_e32 v150, s95, v149
	v_add_u32_e32 v151, s95, v150
	v_add_u32_e32 v152, s95, v151
	v_add_u32_e32 v153, s95, v152
	v_add_u32_e32 v154, s95, v153
	v_add_u32_e32 v155, s95, v154
	s_and_b32 s96, s93, 64
	v_xor_b32_e32 v156, s93, v120
	v_add_u32_e32 v156, s96, v156
	v_mul_u32_u24_e32 v156, 0x4800, v156
	v_lshl_add_u32 v156, v50, 2, v156
	v_add_u32_e32 v157, s95, v156
	v_add_u32_e32 v158, s95, v157
	v_add_u32_e32 v159, s95, v158
	v_add_u32_e32 v160, s95, v159
	v_add_u32_e32 v161, s95, v160
	v_add_u32_e32 v162, s95, v161
	v_add_u32_e32 v163, s95, v162
	v_xor_b32_e32 v164, s93, v118
	v_add_u32_e32 v164, s96, v164
	v_lshlrev_b32_e32 v164, 12, v164
	v_lshl_add_u32 v164, v50, 1, v164
	s_xor_b32 s95, s93, 0x1000
	s_sub_i32 s95, s95, s93
	v_add_u32_e32 v165, s95, v164
	v_add_u32_e32 v166, s95, v165
	v_add_u32_e32 v167, s95, v166
	v_add_u32_e32 v222, v114, v81
	v_add_u32_e32 v223, v114, v82
	v_add_u32_e32 v224, v115, v81
	v_add_u32_e32 v225, v115, v82
	v_add_u32_e32 v226, v95, v81
	v_add_u32_e32 v227, v95, v82
	v_add_u32_e32 v228, s28, v113
	v_add_u32_e32 v229, s47, v113
	s_waitcnt vmcnt(0)
	s_branch .LBB0_501
.LBB0_501:
	s_waitcnt vmcnt(4)
	v_add_u32_e32 v22, 0x4400, v117
	ds_write2st64_b32 v116, v40, v41 offset1:68
	ds_write2_b32 v117, v42, v44 offset1:68
	ds_write2_b32 v22, v43, v45 offset1:68
	ds_write2_b32 v117, v46, v48 offset0:136 offset1:204
	ds_write2_b32 v22, v47, v49 offset0:136 offset1:204
	v_add_u32_e32 v22, 0x400, v117
	ds_write2_b32 v22, v64, v66 offset0:16 offset1:84
	v_add_u32_e32 v22, 0x4800, v117
	ds_write2_b32 v22, v65, v67 offset0:16 offset1:84
	ds_write_b32 v117, v68 offset:1632
	ds_write_b32 v117, v69 offset:19040
	v_lshlrev_b32_e32 v22, 16, v43
	v_lshlrev_b32_e32 v23, 16, v47
	v_lshlrev_b32_e32 v24, 16, v65
	v_lshlrev_b32_e32 v25, 16, v69
	v_and_or_b32 v22, v41, s43, v22
	v_and_or_b32 v23, v45, s43, v23
	v_and_or_b32 v24, v49, s43, v24
	v_and_or_b32 v25, v67, s43, v25
	v_lshrrev_b32_e32 v36, 16, v41
	v_lshrrev_b32_e32 v37, 16, v45
	v_lshrrev_b32_e32 v38, 16, v49
	v_lshrrev_b32_e32 v39, 16, v67
	ds_write_b128 v70, v[22:25] offset:34816
	v_and_or_b32 v36, v43, s44, v36
	v_and_or_b32 v37, v47, s44, v37
	v_and_or_b32 v38, v65, s44, v38
	v_and_or_b32 v39, v69, s44, v39
	s_andn2_b64 vcc, exec, s[26:27]
	ds_write_b128 v70, v[36:39] offset:34960
	s_cbranch_vccnz .LBB0_503
	v_lshlrev_b32_e32 v22, 16, v3
	v_lshlrev_b32_e32 v23, 16, v5
	v_lshlrev_b32_e32 v24, 16, v7
	v_lshlrev_b32_e32 v25, 16, v9
	v_and_or_b32 v22, v2, s43, v22
	v_and_or_b32 v23, v4, s43, v23
	v_and_or_b32 v24, v6, s43, v24
	v_and_or_b32 v25, v8, s43, v25
	v_lshrrev_b32_e32 v36, 16, v2
	v_lshrrev_b32_e32 v37, 16, v4
	v_lshrrev_b32_e32 v38, 16, v6
	v_lshrrev_b32_e32 v39, 16, v8
	v_and_or_b32 v36, v3, s44, v36
	v_and_or_b32 v37, v5, s44, v37
	v_and_or_b32 v38, v7, s44, v38
	v_and_or_b32 v39, v9, s44, v39
	ds_write_b128 v71, v[22:25] offset:53248
	ds_write_b128 v71, v[36:39] offset:53392
.LBB0_503:
	s_waitcnt lgkmcnt(0)
	s_barrier
	s_andn2_b64 vcc, exec, s[30:31]
	s_cbranch_vccnz .Lhg_v0
	s_andn2_b64 vcc, exec, s[34:35]
	s_cbranch_vccnz .Lhg_v1
	ds_read_b128 v[168:171], v126
	ds_read_b128 v[184:187], v121 offset:17408
	ds_read_b128 v[200:203], v122 offset:17408
	ds_read_b128 v[128:131], v123
	ds_read_b128 v[172:175], v126 offset:64
	ds_read_b128 v[188:191], v121 offset:17472
	ds_read_b128 v[204:207], v122 offset:17472
	ds_read_b128 v[132:135], v123 offset:64
	ds_read_b128 v[176:179], v126 offset:128
	ds_read_b128 v[192:195], v121 offset:17536
	ds_read_b128 v[208:211], v122 offset:17536
	ds_read_b128 v[136:139], v123 offset:128
	ds_read_b128 v[180:183], v126 offset:192
	ds_read_b128 v[196:199], v121 offset:17600
	ds_read_b128 v[212:215], v122 offset:17600
	ds_read_b128 v[216:219], v123 offset:192
	s_cmpk_eq_i32 s50, 0xf040
	s_cbranch_scc1 .Lhg_last_b
	s_and_b64 s[94:95], exec, s[2:3]
	s_cselect_b32 s94, s46, s49
	s_ashr_i32 s95, s94, 31
	s_lshl_b64 s[94:95], s[94:95], 12
	v_lshl_add_u64 v[22:23], v[30:31], 0, s[94:95]
	global_load_dwordx4 v[22:25], v[22:23], off
	global_load_dword v40, v140, s[54:55]
	global_load_dword v41, v148, s[56:57]
	global_load_dword v42, v141, s[54:55]
	global_load_dword v43, v149, s[56:57]
	global_load_dword v44, v142, s[54:55]
	global_load_dword v45, v150, s[56:57]
	global_load_dword v46, v143, s[54:55]
	global_load_dword v47, v151, s[56:57]
	global_load_dword v48, v144, s[54:55]
	global_load_dword v49, v152, s[56:57]
	global_load_dword v64, v145, s[54:55]
	global_load_dword v65, v153, s[56:57]
	global_load_dword v66, v146, s[54:55]
	global_load_dword v67, v154, s[56:57]
	global_load_dword v68, v147, s[54:55]
	global_load_dword v69, v155, s[56:57]
	s_add_u32 s54, s54, s62
	s_addc_u32 s55, s55, s93
	s_add_u32 s56, s56, s63
	s_addc_u32 s57, s57, s93
	s_andn2_b64 vcc, exec, s[26:27]
	s_cbranch_vccnz .Lhg_ld_done_b
	global_load_dword v2, v156, s[58:59] offset:2048 nt
	global_load_dword v3, v157, s[58:59] offset:2048 nt
	global_load_dword v4, v158, s[58:59] offset:2048 nt
	global_load_dword v5, v159, s[58:59] offset:2048 nt
	global_load_dword v6, v160, s[58:59] offset:2048 nt
	global_load_dword v7, v161, s[58:59] offset:2048 nt
	global_load_dword v8, v162, s[58:59] offset:2048 nt
	global_load_dword v9, v163, s[58:59] offset:2048 nt
	s_add_u32 s58, s58, s63
	s_addc_u32 s59, s59, s93
	s_branch .Lhg_ld_done_b

.Lhg_ld_done_b:
	v_pk_mul_f32 v[20:21], v[12:13], v[20:21]
	v_pk_mul_f32 v[18:19], v[10:11], v[18:19]
	v_pk_mul_f32 v[12:13], v[12:13], v[16:17]
	v_pk_mul_f32 v[10:11], v[10:11], v[14:15]
	s_add_i32 s49, s49, -1
	s_add_i32 s46, s46, 1
	s_waitcnt lgkmcnt(14)
	v_mfma_f32_16x16x32_bf16 v[36:39], v[184:187], v[168:171], 0
	s_waitcnt lgkmcnt(13)
	v_mfma_f32_16x16x32_bf16 v[26:29], v[200:203], v[168:171], 0
	s_waitcnt lgkmcnt(12)
	v_mfma_f32_16x16x32_bf16 v[32:35], v[168:171], v[128:131], 0
	s_waitcnt lgkmcnt(10)
	v_mfma_f32_16x16x32_bf16 v[36:39], v[188:191], v[172:175], v[36:39]
	s_waitcnt lgkmcnt(9)
	v_mfma_f32_16x16x32_bf16 v[26:29], v[204:207], v[172:175], v[26:29]
	s_waitcnt lgkmcnt(8)
	v_mfma_f32_16x16x32_bf16 v[32:35], v[172:175], v[132:135], v[32:35]
	s_waitcnt lgkmcnt(6)
	v_mfma_f32_16x16x32_bf16 v[36:39], v[192:195], v[176:179], v[36:39]
	s_waitcnt lgkmcnt(5)
	v_mfma_f32_16x16x32_bf16 v[26:29], v[208:211], v[176:179], v[26:29]
	s_waitcnt lgkmcnt(4)
	v_mfma_f32_16x16x32_bf16 v[32:35], v[176:179], v[136:139], v[32:35]
	s_waitcnt lgkmcnt(2)
	v_mfma_f32_16x16x32_bf16 v[36:39], v[196:199], v[180:183], v[36:39]
	s_waitcnt lgkmcnt(1)
	v_mfma_f32_16x16x32_bf16 v[26:29], v[212:215], v[180:183], v[26:29]
	s_waitcnt lgkmcnt(0)
	v_mfma_f32_16x16x32_bf16 v[32:35], v[180:183], v[216:219], v[32:35]
	s_nop 7
	v_cndmask_b32_e64 v36, v36, 0, s[4:5]
	v_cndmask_b32_e64 v37, 0, v37, s[6:7]
	v_cndmask_b32_e64 v38, v38, 0, s[8:9]
	v_cndmask_b32_e64 v39, v39, 0, s[10:11]
	v_cvt_pk_bf16_f32 v36, v36, v37
	v_cvt_pk_bf16_f32 v37, v38, v39
	ds_write_b64 v228, v[36:37] offset:57856
	v_cndmask_b32_e64 v26, v26, 0, s[12:13]
	v_cndmask_b32_e64 v27, 0, v27, s[14:15]
	v_cndmask_b32_e64 v28, v28, 0, s[16:17]
	v_cndmask_b32_e64 v29, v29, 0, s[18:19]
	v_cvt_pk_bf16_f32 v26, v26, v27
	v_cvt_pk_bf16_f32 v27, v28, v29
	ds_write_b64 v229, v[26:27] offset:57856
	s_branch .Lhg_p3
.Lhg_v1:
	ds_read_b128 v[168:171], v126
	ds_read_b128 v[184:187], v121 offset:17408
	ds_read_b128 v[128:131], v123
	ds_read_b128 v[172:175], v126 offset:64
	ds_read_b128 v[188:191], v121 offset:17472
	ds_read_b128 v[132:135], v123 offset:64
	ds_read_b128 v[176:179], v126 offset:128
	ds_read_b128 v[192:195], v121 offset:17536
	ds_read_b128 v[136:139], v123 offset:128
	ds_read_b128 v[180:183], v126 offset:192
	ds_read_b128 v[196:199], v121 offset:17600
	ds_read_b128 v[216:219], v123 offset:192
	s_cmpk_eq_i32 s50, 0xf040
	s_cbranch_scc1 .Lhg_last_a
	s_and_b64 s[94:95], exec, s[2:3]
	s_cselect_b32 s94, s46, s49
	s_ashr_i32 s95, s94, 31
	s_lshl_b64 s[94:95], s[94:95], 12
	v_lshl_add_u64 v[22:23], v[30:31], 0, s[94:95]
	global_load_dwordx4 v[22:25], v[22:23], off
	global_load_dword v40, v140, s[54:55]
	global_load_dword v41, v148, s[56:57]
	global_load_dword v42, v141, s[54:55]
	global_load_dword v43, v149, s[56:57]
	global_load_dword v44, v142, s[54:55]
	global_load_dword v45, v150, s[56:57]
	global_load_dword v46, v143, s[54:55]
	global_load_dword v47, v151, s[56:57]
	global_load_dword v48, v144, s[54:55]
	global_load_dword v49, v152, s[56:57]
	global_load_dword v64, v145, s[54:55]
	global_load_dword v65, v153, s[56:57]
	global_load_dword v66, v146, s[54:55]
	global_load_dword v67, v154, s[56:57]
	global_load_dword v68, v147, s[54:55]
	global_load_dword v69, v155, s[56:57]
	s_add_u32 s54, s54, s62
	s_addc_u32 s55, s55, s93
	s_add_u32 s56, s56, s63
	s_addc_u32 s57, s57, s93
	s_andn2_b64 vcc, exec, s[26:27]
	s_cbranch_vccnz .Lhg_ld_done_a
	global_load_dword v2, v156, s[58:59] offset:2048 nt
	global_load_dword v3, v157, s[58:59] offset:2048 nt
	global_load_dword v4, v158, s[58:59] offset:2048 nt
	global_load_dword v5, v159, s[58:59] offset:2048 nt
	global_load_dword v6, v160, s[58:59] offset:2048 nt
	global_load_dword v7, v161, s[58:59] offset:2048 nt
	global_load_dword v8, v162, s[58:59] offset:2048 nt
	global_load_dword v9, v163, s[58:59] offset:2048 nt
	s_add_u32 s58, s58, s63
	s_addc_u32 s59, s59, s93
	s_branch .Lhg_ld_done_a

.Lhg_ld_done_a:
	v_pk_mul_f32 v[20:21], v[12:13], v[20:21]
	v_pk_mul_f32 v[18:19], v[10:11], v[18:19]
	v_pk_mul_f32 v[12:13], v[12:13], v[16:17]
	v_pk_mul_f32 v[10:11], v[10:11], v[14:15]
	s_add_i32 s49, s49, -1
	s_add_i32 s46, s46, 1
	s_waitcnt lgkmcnt(10)
	v_mfma_f32_16x16x32_bf16 v[36:39], v[184:187], v[168:171], 0
	s_waitcnt lgkmcnt(9)
	v_mfma_f32_16x16x32_bf16 v[32:35], v[168:171], v[128:131], 0
	s_waitcnt lgkmcnt(7)
	v_mfma_f32_16x16x32_bf16 v[36:39], v[188:191], v[172:175], v[36:39]
	s_waitcnt lgkmcnt(6)
	v_mfma_f32_16x16x32_bf16 v[32:35], v[172:175], v[132:135], v[32:35]
	s_waitcnt lgkmcnt(4)
	v_mfma_f32_16x16x32_bf16 v[36:39], v[192:195], v[176:179], v[36:39]
	s_waitcnt lgkmcnt(3)
	v_mfma_f32_16x16x32_bf16 v[32:35], v[176:179], v[136:139], v[32:35]
	s_waitcnt lgkmcnt(1)
	v_mfma_f32_16x16x32_bf16 v[36:39], v[196:199], v[180:183], v[36:39]
	s_waitcnt lgkmcnt(0)
	v_mfma_f32_16x16x32_bf16 v[32:35], v[180:183], v[216:219], v[32:35]
	s_nop 7
	v_cndmask_b32_e64 v36, v36, 0, s[4:5]
	v_cndmask_b32_e64 v37, 0, v37, s[6:7]
	v_cndmask_b32_e64 v38, v38, 0, s[8:9]
	v_cndmask_b32_e64 v39, v39, 0, s[10:11]
	v_cvt_pk_bf16_f32 v36, v36, v37
	v_cvt_pk_bf16_f32 v37, v38, v39
	ds_write_b64 v228, v[36:37] offset:57856
	v_mov_b32_e32 v26, 0
	v_mov_b32_e32 v27, 0
	ds_write_b64 v229, v[26:27] offset:57856
	s_branch .Lhg_p3
.Lhg_v0:
	ds_read_b128 v[168:171], v126
	ds_read_b128 v[128:131], v123
	ds_read_b128 v[172:175], v126 offset:64
	ds_read_b128 v[132:135], v123 offset:64
	ds_read_b128 v[176:179], v126 offset:128
	ds_read_b128 v[136:139], v123 offset:128
	ds_read_b128 v[180:183], v126 offset:192
	ds_read_b128 v[216:219], v123 offset:192
	s_cmpk_eq_i32 s50, 0xf040
	s_cbranch_scc1 .Lhg_last_n
	s_and_b64 s[94:95], exec, s[2:3]
	s_cselect_b32 s94, s46, s49
	s_ashr_i32 s95, s94, 31
	s_lshl_b64 s[94:95], s[94:95], 12
	v_lshl_add_u64 v[22:23], v[30:31], 0, s[94:95]
	global_load_dwordx4 v[22:25], v[22:23], off
	global_load_dword v40, v140, s[54:55]
	global_load_dword v41, v148, s[56:57]
	global_load_dword v42, v141, s[54:55]
	global_load_dword v43, v149, s[56:57]
	global_load_dword v44, v142, s[54:55]
	global_load_dword v45, v150, s[56:57]
	global_load_dword v46, v143, s[54:55]
	global_load_dword v47, v151, s[56:57]
	global_load_dword v48, v144, s[54:55]
	global_load_dword v49, v152, s[56:57]
	global_load_dword v64, v145, s[54:55]
	global_load_dword v65, v153, s[56:57]
	global_load_dword v66, v146, s[54:55]
	global_load_dword v67, v154, s[56:57]
	global_load_dword v68, v147, s[54:55]
	global_load_dword v69, v155, s[56:57]
	s_add_u32 s54, s54, s62
	s_addc_u32 s55, s55, s93
	s_add_u32 s56, s56, s63
	s_addc_u32 s57, s57, s93
	s_andn2_b64 vcc, exec, s[26:27]
	s_cbranch_vccnz .Lhg_ld_done_n
	global_load_dword v2, v156, s[58:59] offset:2048 nt
	global_load_dword v3, v157, s[58:59] offset:2048 nt
	global_load_dword v4, v158, s[58:59] offset:2048 nt
	global_load_dword v5, v159, s[58:59] offset:2048 nt
	global_load_dword v6, v160, s[58:59] offset:2048 nt
	global_load_dword v7, v161, s[58:59] offset:2048 nt
	global_load_dword v8, v162, s[58:59] offset:2048 nt
	global_load_dword v9, v163, s[58:59] offset:2048 nt
	s_add_u32 s58, s58, s63
	s_addc_u32 s59, s59, s93
	s_branch .Lhg_ld_done_n

.Lhg_ld_done_n:
	v_pk_mul_f32 v[20:21], v[12:13], v[20:21]
	v_pk_mul_f32 v[18:19], v[10:11], v[18:19]
	v_pk_mul_f32 v[12:13], v[12:13], v[16:17]
	v_pk_mul_f32 v[10:11], v[10:11], v[14:15]
	s_add_i32 s49, s49, -1
	s_add_i32 s46, s46, 1
	s_waitcnt lgkmcnt(6)
	v_mfma_f32_16x16x32_bf16 v[32:35], v[168:171], v[128:131], 0
	s_waitcnt lgkmcnt(4)
	v_mfma_f32_16x16x32_bf16 v[32:35], v[172:175], v[132:135], v[32:35]
	s_waitcnt lgkmcnt(2)
	v_mfma_f32_16x16x32_bf16 v[32:35], v[176:179], v[136:139], v[32:35]
	s_waitcnt lgkmcnt(0)
	v_mfma_f32_16x16x32_bf16 v[32:35], v[180:183], v[216:219], v[32:35]
	v_mov_b32_e32 v26, 0
	v_mov_b32_e32 v27, 0
	ds_write_b64 v228, v[26:27] offset:57856
	ds_write_b64 v229, v[26:27] offset:57856
.Lhg_p3:
	s_waitcnt lgkmcnt(0)
	s_barrier
	ds_read_b128 v[168:171], v124 offset:57856
	ds_read_b128 v[172:175], v222 offset:53248
	ds_read_b128 v[176:179], v224 offset:34816
	ds_read_b128 v[180:183], v226 offset:53248
	ds_read_b128 v[184:187], v226 offset:55552
	ds_read_b128 v[188:191], v124 offset:57920
	ds_read_b128 v[192:195], v223 offset:53248
	ds_read_b128 v[196:199], v225 offset:34816
	ds_read_b128 v[200:203], v227 offset:53248
	ds_read_b128 v[204:207], v227 offset:55552
	s_waitcnt lgkmcnt(8)
	v_mfma_f32_16x16x32_bf16 v[32:35], v[168:171], v[172:175], v[32:35]
	s_waitcnt lgkmcnt(6)
	v_mfma_f32_16x16x32_bf16 v[18:21], v[176:179], v[180:183], v[18:21]
	s_waitcnt lgkmcnt(5)
	v_mfma_f32_16x16x32_bf16 v[10:13], v[176:179], v[184:187], v[10:13]
	s_waitcnt lgkmcnt(3)
	v_mfma_f32_16x16x32_bf16 v[32:35], v[188:191], v[192:195], v[32:35]
	s_waitcnt lgkmcnt(1)
	v_mfma_f32_16x16x32_bf16 v[18:21], v[196:199], v[200:203], v[18:21]
	s_waitcnt lgkmcnt(0)
	v_mfma_f32_16x16x32_bf16 v[14:17], v[196:199], v[204:207], v[10:13]
	s_nop 5
	v_cvt_pk_bf16_f32 v128, v32, s0
	v_cvt_pk_bf16_f32 v129, v33, s0
	v_cvt_pk_bf16_f32 v130, v34, s0
	v_cvt_pk_bf16_f32 v131, v35, s0
	global_store_short v164, v128, s[60:61]
	global_store_short v165, v129, s[60:61]
	global_store_short v166, v130, s[60:61]
	global_store_short v167, v131, s[60:61]
	s_add_u32 s60, s60, s92
	s_addc_u32 s61, s61, s93
	s_andn2_b64 vcc, exec, s[26:27]
	s_cbranch_vccnz .Lhg_dw_hi
	s_waitcnt vmcnt(28)
	s_branch .Lhg_dw_done
.Lhg_dw_hi:
	s_waitcnt vmcnt(20)
.Lhg_dw_done:
	v_pk_mul_f32 v[36:37], v[24:25], v[20:21]
	v_pk_mul_f32 v[38:39], v[22:23], v[18:19]
	v_pk_mul_f32 v[26:27], v[24:25], v[16:17]
	v_pk_mul_f32 v[28:29], v[22:23], v[14:15]
	s_nop 0
	v_cvt_pk_bf16_f32 v38, v38, v39
	v_cvt_pk_bf16_f32 v39, v36, v37
	ds_write_b64 v125, v[38:39]
	v_cvt_pk_bf16_f32 v28, v28, v29
	v_cvt_pk_bf16_f32 v29, v26, v27
	ds_write_b64 v125, v[28:29] offset:4352
	s_waitcnt lgkmcnt(0)
	s_barrier
	v_mov_b64_e32 v[10:11], v[22:23]
	v_mov_b64_e32 v[12:13], v[24:25]
	s_sub_i32 s50, s50, 64
	s_cmpk_eq_i32 s50, 0xf000
	s_cbranch_scc1 .LBB0_436
	s_branch .LBB0_501
